# flat-release grid barrier: last arriver bumps every XCD's XGEN directly, LDS barrier counter instead of divisions (on k07)
# baseline (speedup 1.0000x reference)
.LBB0_12:
	v_writelane_b32 v254, s0, 0
	s_nop 1
	v_writelane_b32 v254, s1, 1
	s_lshr_b32 s0, s33, 6
	s_add_u32 s78, s40, 0x1f700000
	v_writelane_b32 v254, s0, 2
	s_addc_u32 s79, s41, 0
	s_sub_i32 s0, s43, s42
	s_cmp_lt_i32 s0, 2
	s_cbranch_scc1 .LBB0_17
	v_readlane_b32 s0, v254, 2
	v_mbcnt_lo_u32_b32 v0, -1, 0
	v_mbcnt_hi_u32_b32 v0, -1, v0
	s_lshl_b32 s0, s0, 6
	v_sub_u32_e32 v0, 0, v0
	v_cmp_eq_u32_e32 vcc, s0, v0
	s_and_saveexec_b64 s[0:1], vcc
	s_cbranch_execz .LBB0_16
	s_add_i32 s4, 0, 0x20000
	v_mov_b32_e32 v0, 0
	v_mov_b32_e32 v1, s4
	s_add_i32 s4, 0, 0x20004
	s_mov_b64 s[2:3], exec
	ds_write_b32 v1, v0
	v_mov_b32_e32 v1, s4
	ds_write_b32 v1, v0
	ds_write_b32 v1, v0 offset:4
	v_mbcnt_lo_u32_b32 v0, s2, 0
	v_mbcnt_hi_u32_b32 v0, s3, v0
	v_cmp_eq_u32_e32 vcc, 0, v0
	s_getreg_b32 s4, hwreg(HW_REG_XCC_ID, 0, 4)
	s_and_b64 s[6:7], exec, vcc
	s_mov_b64 exec, s[6:7]
	s_cbranch_execz .LBB0_16
	s_lshl_b32 s4, s4, 8
	s_and_b32 s4, s4, 0xf00
	s_bcnt1_i32_b64 s2, s[2:3]
	v_mov_b32_e32 v0, s4
	v_mov_b32_e32 v1, s2
	global_atomic_add v0, v1, s[78:79] offset:1024

.LBB0_92:
	s_waitcnt vmcnt(0) lgkmcnt(0)
	v_readlane_b32 s2, v254, 0
	v_readlane_b32 s3, v254, 1
	v_mov_b32_e32 v0, 0x20000
	s_load_dwordx2 s[4:5], s[2:3], 0xe0
	s_getreg_b32 s6, hwreg(20, 0, 4)
	ds_read_b64 v[2:3], v0
	ds_read_b32 v4, v0 offset:8
	s_and_b32 s6, s6, 15
	s_lshl_b32 s6, s6, 8
	v_mov_b32_e32 v1, 0x1000
	v_mov_b32_e32 v5, 1
	s_waitcnt lgkmcnt(0)
	s_add_u32 s4, s4, 0x1f700000
	s_addc_u32 s5, s5, 0
	s_add_u32 s6, s4, s6
	s_addc_u32 s7, s5, 0
	v_readfirstlane_b32 s2, v2
	v_readfirstlane_b32 s3, v3
	v_readfirstlane_b32 s98, v4
	global_atomic_add v2, v1, v5, s[6:7] offset:1024 sc0
	s_nop 1
	s_add_u32 s99, s98, 1
	s_mul_i32 s100, s99, s2
	s_waitcnt vmcnt(0)
	v_readfirstlane_b32 s101, v2
	s_nop 1
	s_add_u32 s101, s101, 1
	s_cmp_lg_u32 s101, s100
	s_cbranch_scc1 .Lxb_spin_0
	buffer_wbl2 sc1
	s_mul_i32 s100, s99, s3
	v_mov_b32_e32 v1, 0x3000
	s_waitcnt vmcnt(0)
	global_atomic_add v2, v1, v5, s[4:5] offset:1024 sc0
	s_waitcnt vmcnt(0)
	v_readfirstlane_b32 s101, v2
	s_nop 1
	s_add_u32 s101, s101, 1
	s_cmp_lg_u32 s101, s100
	s_cbranch_scc1 .Lxb_spin_0
	v_mov_b32_e32 v1, 0x2400
	global_atomic_add v1, v5, s[4:5]
	global_atomic_add v1, v5, s[4:5] offset:256
	global_atomic_add v1, v5, s[4:5] offset:512
	global_atomic_add v1, v5, s[4:5] offset:768
	global_atomic_add v1, v5, s[4:5] offset:1024
	global_atomic_add v1, v5, s[4:5] offset:1280
	global_atomic_add v1, v5, s[4:5] offset:1536
	global_atomic_add v1, v5, s[4:5] offset:1792
	global_atomic_add v1, v5, s[4:5] offset:2048
	global_atomic_add v1, v5, s[4:5] offset:2304
	global_atomic_add v1, v5, s[4:5] offset:2560
	global_atomic_add v1, v5, s[4:5] offset:2816
	global_atomic_add v1, v5, s[4:5] offset:3072
	global_atomic_add v1, v5, s[4:5] offset:3328
	global_atomic_add v1, v5, s[4:5] offset:3584
	global_atomic_add v1, v5, s[4:5] offset:3840
	s_branch .Lxb_done_0
.Lxb_spin_0:
	v_mov_b32_e32 v1, 0x2000
	s_mov_b32 s8, 0
.Lxb_poll_0:
	global_load_dword v2, v1, s[6:7] offset:1024 sc1
	s_waitcnt vmcnt(0)
	v_readfirstlane_b32 s101, v2
	s_nop 1
	s_cmp_lg_u32 s101, s98
	s_cbranch_scc1 .Lxb_done_0
	s_add_u32 s8, s8, 1
	s_cmp_lt_u32 s8, 0x10000
	s_cbranch_scc0 .Lxb_done_0
	s_sleep 1
	s_branch .Lxb_poll_0
.Lxb_done_0:
	s_waitcnt vmcnt(0)
	buffer_inv sc1
	v_mov_b32_e32 v2, s99
	ds_write_b32 v0, v2 offset:8
	s_waitcnt vmcnt(0)

.Lxb_done_11:
	s_waitcnt vmcnt(0)
	buffer_inv sc1
	v_mov_b32_e32 v2, s99
	ds_write_b32 v0, v2 offset:8
	s_waitcnt vmcnt(0)
	s_branch .LBB0_697

.LBB0_1423:
	s_waitcnt vmcnt(0) lgkmcnt(0)
	v_readlane_b32 s4, v254, 0
	v_readlane_b32 s5, v254, 1
	v_mov_b32_e32 v0, 0x20000
	s_load_dwordx2 s[6:7], s[4:5], 0xe0
	s_getreg_b32 s8, hwreg(20, 0, 4)
	ds_read_b64 v[2:3], v0
	ds_read_b32 v4, v0 offset:8
	s_and_b32 s8, s8, 15
	s_lshl_b32 s8, s8, 8
	v_mov_b32_e32 v1, 0x1000
	v_mov_b32_e32 v5, 1
	s_waitcnt lgkmcnt(0)
	s_add_u32 s6, s6, 0x1f700000
	s_addc_u32 s7, s7, 0
	s_add_u32 s8, s6, s8
	s_addc_u32 s9, s7, 0
	v_readfirstlane_b32 s4, v2
	v_readfirstlane_b32 s5, v3
	v_readfirstlane_b32 s98, v4
	global_atomic_add v2, v1, v5, s[8:9] offset:1024 sc0
	s_nop 1
	s_add_u32 s99, s98, 1
	s_mul_i32 s100, s99, s4
	s_waitcnt vmcnt(0)
	v_readfirstlane_b32 s101, v2
	s_nop 1
	s_add_u32 s101, s101, 1
	s_cmp_lg_u32 s101, s100
	s_cbranch_scc1 .Lxb_spin_16
	buffer_wbl2 sc1
	s_mul_i32 s100, s99, s5
	v_mov_b32_e32 v1, 0x3000
	s_waitcnt vmcnt(0)
	global_atomic_add v2, v1, v5, s[6:7] offset:1024 sc0
	s_waitcnt vmcnt(0)
	v_readfirstlane_b32 s101, v2
	s_nop 1
	s_add_u32 s101, s101, 1
	s_cmp_lg_u32 s101, s100
	s_cbranch_scc1 .Lxb_spin_16
	v_mov_b32_e32 v1, 0x2400
	global_atomic_add v1, v5, s[6:7]
	global_atomic_add v1, v5, s[6:7] offset:256
	global_atomic_add v1, v5, s[6:7] offset:512
	global_atomic_add v1, v5, s[6:7] offset:768
	global_atomic_add v1, v5, s[6:7] offset:1024
	global_atomic_add v1, v5, s[6:7] offset:1280
	global_atomic_add v1, v5, s[6:7] offset:1536
	global_atomic_add v1, v5, s[6:7] offset:1792
	global_atomic_add v1, v5, s[6:7] offset:2048
	global_atomic_add v1, v5, s[6:7] offset:2304
	global_atomic_add v1, v5, s[6:7] offset:2560
	global_atomic_add v1, v5, s[6:7] offset:2816
	global_atomic_add v1, v5, s[6:7] offset:3072
	global_atomic_add v1, v5, s[6:7] offset:3328
	global_atomic_add v1, v5, s[6:7] offset:3584
	global_atomic_add v1, v5, s[6:7] offset:3840
	s_branch .Lxb_done_16
.Lxb_spin_16:
	v_mov_b32_e32 v1, 0x2000
	s_mov_b32 s10, 0
.Lxb_poll_16:
	global_load_dword v2, v1, s[8:9] offset:1024 sc1
	s_waitcnt vmcnt(0)
	v_readfirstlane_b32 s101, v2
	s_nop 1
	s_cmp_lg_u32 s101, s98
	s_cbranch_scc1 .Lxb_done_16
	s_add_u32 s10, s10, 1
	s_cmp_lt_u32 s10, 0x10000
	s_cbranch_scc0 .Lxb_done_16
	s_sleep 1
	s_branch .Lxb_poll_16

.LBB0_1525:
	s_waitcnt vmcnt(0) lgkmcnt(0)
	v_readlane_b32 s8, v254, 0
	v_readlane_b32 s9, v254, 1
	v_mov_b32_e32 v48, 0x20000
	s_load_dwordx2 s[10:11], s[8:9], 0xe0
	s_getreg_b32 s20, hwreg(20, 0, 4)
	ds_read_b64 v[50:51], v48
	ds_read_b32 v52, v48 offset:8
	s_and_b32 s20, s20, 15
	s_lshl_b32 s20, s20, 8
	v_mov_b32_e32 v49, 0x1000
	v_mov_b32_e32 v53, 1
	s_waitcnt lgkmcnt(0)
	s_add_u32 s10, s10, 0x1f700000
	s_addc_u32 s11, s11, 0
	s_add_u32 s20, s10, s20
	s_addc_u32 s21, s11, 0
	v_readfirstlane_b32 s8, v50
	v_readfirstlane_b32 s9, v51
	v_readfirstlane_b32 s98, v52
	global_atomic_add v50, v49, v53, s[20:21] offset:1024 sc0
	s_nop 1
	s_add_u32 s99, s98, 1
	s_mul_i32 s100, s99, s8
	s_waitcnt vmcnt(0)
	v_readfirstlane_b32 s101, v50
	s_nop 1
	s_add_u32 s101, s101, 1
	s_cmp_lg_u32 s101, s100
	s_cbranch_scc1 .Lxb_spin_17
	buffer_wbl2 sc1
	s_mul_i32 s100, s99, s9
	v_mov_b32_e32 v49, 0x3000
	s_waitcnt vmcnt(0)
	global_atomic_add v50, v49, v53, s[10:11] offset:1024 sc0
	s_waitcnt vmcnt(0)
	v_readfirstlane_b32 s101, v50
	s_nop 1
	s_add_u32 s101, s101, 1
	s_cmp_lg_u32 s101, s100
	s_cbranch_scc1 .Lxb_spin_17
	v_mov_b32_e32 v49, 0x2400
	global_atomic_add v49, v53, s[10:11]
	global_atomic_add v49, v53, s[10:11] offset:256
	global_atomic_add v49, v53, s[10:11] offset:512
	global_atomic_add v49, v53, s[10:11] offset:768
	global_atomic_add v49, v53, s[10:11] offset:1024
	global_atomic_add v49, v53, s[10:11] offset:1280
	global_atomic_add v49, v53, s[10:11] offset:1536
	global_atomic_add v49, v53, s[10:11] offset:1792
	global_atomic_add v49, v53, s[10:11] offset:2048
	global_atomic_add v49, v53, s[10:11] offset:2304
	global_atomic_add v49, v53, s[10:11] offset:2560
	global_atomic_add v49, v53, s[10:11] offset:2816
	global_atomic_add v49, v53, s[10:11] offset:3072
	global_atomic_add v49, v53, s[10:11] offset:3328
	global_atomic_add v49, v53, s[10:11] offset:3584
	global_atomic_add v49, v53, s[10:11] offset:3840
	s_branch .Lxb_done_17
.Lxb_spin_17:
	v_mov_b32_e32 v49, 0x2000
	s_mov_b32 s22, 0
.Lxb_poll_17:
	global_load_dword v50, v49, s[20:21] offset:1024 sc1
	s_waitcnt vmcnt(0)
	v_readfirstlane_b32 s101, v50
	s_nop 1
	s_cmp_lg_u32 s101, s98
	s_cbranch_scc1 .Lxb_done_17
	s_add_u32 s22, s22, 1
	s_cmp_lt_u32 s22, 0x10000
	s_cbranch_scc0 .Lxb_done_17
	s_sleep 1
	s_branch .Lxb_poll_17
.Lxb_done_17:
	s_waitcnt vmcnt(0)
	buffer_inv sc1
	v_mov_b32_e32 v50, s99
	ds_write_b32 v48, v50 offset:8
	s_waitcnt vmcnt(0)
